# epilogue de-serialisation: residual-update epilogue (DOWN/RECOUT/WO) issues the second row-half's XB/XL loads during the first half's compute into dead registers instead of after it; otherwise as v65
# baseline (speedup 1.0000x reference)
.LBB0_586:
	v_add_co_u32_e32 v240, vcc, 0x20000, v172
	v_addc_co_u32_e32 v241, vcc, 0, v173, vcc
	v_lshrrev_b64 v[240:241], 1, v[240:241]
	v_lshl_add_u64 v[240:241], s[12:13], 0, v[240:241]
	global_load_dword v233, v[240:241], off
	v_add_co_u32_e32 v240, vcc, 0x20080, v172
	v_addc_co_u32_e32 v241, vcc, 0, v173, vcc
	v_lshrrev_b64 v[240:241], 1, v[240:241]
	v_lshl_add_u64 v[240:241], s[12:13], 0, v[240:241]
	global_load_dword v234, v[240:241], off
	v_add_co_u32_e32 v240, vcc, 0x24000, v172
	v_addc_co_u32_e32 v241, vcc, 0, v173, vcc
	v_lshrrev_b64 v[240:241], 1, v[240:241]
	v_lshl_add_u64 v[240:241], s[12:13], 0, v[240:241]
	global_load_dword v235, v[240:241], off
	v_add_co_u32_e32 v240, vcc, 0x24080, v172
	v_addc_co_u32_e32 v241, vcc, 0, v173, vcc
	v_lshrrev_b64 v[240:241], 1, v[240:241]
	v_lshl_add_u64 v[240:241], s[12:13], 0, v[240:241]
	global_load_dword v249, v[240:241], off
	v_add_co_u32_e32 v240, vcc, 0x28000, v172
	v_addc_co_u32_e32 v241, vcc, 0, v173, vcc
	v_lshrrev_b64 v[240:241], 1, v[240:241]
	v_lshl_add_u64 v[240:241], s[12:13], 0, v[240:241]
	global_load_dword v250, v[240:241], off
	v_add_co_u32_e32 v240, vcc, 0x28080, v172
	v_addc_co_u32_e32 v241, vcc, 0, v173, vcc
	v_lshrrev_b64 v[240:241], 1, v[240:241]
	v_lshl_add_u64 v[240:241], s[12:13], 0, v[240:241]
	global_load_dword v251, v[240:241], off
	v_add_co_u32_e32 v240, vcc, 0x2c000, v172
	v_addc_co_u32_e32 v241, vcc, 0, v173, vcc
	v_lshrrev_b64 v[240:241], 1, v[240:241]
	v_lshl_add_u64 v[240:241], s[12:13], 0, v[240:241]
	global_load_dword v147, v[240:241], off
	v_add_co_u32_e32 v240, vcc, 0x2c080, v172
	v_addc_co_u32_e32 v241, vcc, 0, v173, vcc
	v_lshrrev_b64 v[240:241], 1, v[240:241]
	v_lshl_add_u64 v[240:241], s[12:13], 0, v[240:241]
	global_load_dword v218, v[240:241], off
	v_add_co_u32_e32 v244, vcc, 0x40000, v170
	v_addc_co_u32_e32 v245, vcc, 0, v171, vcc
	global_load_dwordx4 v[240:243], v[244:245], off
	global_load_dwordx4 v[244:247], v[244:245], off offset:256
	v_add_co_u32_e32 v198, vcc, 0x48000, v170
	v_addc_co_u32_e32 v199, vcc, 0, v171, vcc
	global_load_dwordx4 v[152:155], v[198:199], off
	global_load_dwordx4 v[198:201], v[198:199], off offset:256
	v_add_co_u32_e32 v220, vcc, 0x50000, v170
	v_addc_co_u32_e32 v221, vcc, 0, v171, vcc
	global_load_dwordx4 v[202:205], v[220:221], off
	global_load_dwordx4 v[220:223], v[220:221], off offset:256
	v_add_co_u32_e32 v228, vcc, 0x58000, v170
	v_addc_co_u32_e32 v229, vcc, 0, v171, vcc
	global_load_dwordx4 v[224:227], v[228:229], off
	global_load_dwordx4 v[228:231], v[228:229], off offset:256
	s_lshl_b32 s54, s34, 2
	v_cndmask_b32_e64 v128, 0, 1, s[18:19]
	v_cmp_ne_u32_e64 s[44:45], 1, v128
	s_andn2_b64 vcc, exec, s[18:19]
	s_ashr_i32 s55, s54, 31
	s_cbranch_vccnz .LBB0_590
	ds_bpermute_b32 v128, v209, v219
	s_waitcnt lgkmcnt(0)
	v_add_f32_e32 v128, v219, v128
	ds_bpermute_b32 v129, v210, v128
	s_and_saveexec_b64 s[20:21], s[38:39]
	s_cbranch_execz .LBB0_589
	v_lshlrev_b64 v[130:131], 6, v[166:167]
	v_lshl_add_u64 v[130:131], s[4:5], 0, v[130:131]
	v_lshl_add_u64 v[130:131], s[54:55], 2, v[130:131]
	s_lshl_b32 s34, s65, 2
	v_lshl_add_u64 v[130:131], v[130:131], 0, s[34:35]
	s_waitcnt lgkmcnt(0)
	v_add_f32_e32 v128, v128, v129
	flat_store_dword v[130:131], v128

.LBB0_626:
	s_mov_b64 s[20:21], 0x20000
	v_lshl_add_u64 v[122:123], v[172:173], 0, s[20:21]
	v_add_co_u32_e32 v64, vcc, 0x40000, v170
	s_mov_b64 s[20:21], 0x20080
	s_waitcnt lgkmcnt(0)
	v_addc_co_u32_e32 v65, vcc, 0, v171, vcc
	v_lshl_add_u64 v[118:119], v[172:173], 0, s[20:21]
	s_mov_b64 s[20:21], 0x24000
	v_lshrrev_b64 v[64:65], 1, v[118:119]
	v_lshl_add_u64 v[114:115], v[172:173], 0, s[20:21]
	s_mov_b32 s20, 0x48000
	v_lshl_add_u64 v[116:117], s[12:13], 0, v[64:65]
	v_add_co_u32_e32 v64, vcc, s20, v170
	s_mov_b64 s[20:21], 0x24080
	s_nop 0
	v_addc_co_u32_e32 v65, vcc, 0, v171, vcc
	v_lshl_add_u64 v[110:111], v[172:173], 0, s[20:21]
	s_mov_b64 s[20:21], 0x28000
	v_lshrrev_b64 v[64:65], 1, v[110:111]
	v_lshl_add_u64 v[106:107], v[172:173], 0, s[20:21]
	s_mov_b32 s20, 0x50000
	v_lshl_add_u64 v[108:109], s[12:13], 0, v[64:65]
	v_add_co_u32_e32 v64, vcc, s20, v170
	s_mov_b64 s[20:21], 0x28080
	s_nop 0
	v_addc_co_u32_e32 v65, vcc, 0, v171, vcc
	v_lshl_add_u64 v[102:103], v[172:173], 0, s[20:21]
	s_mov_b64 s[20:21], 0x2c000
	v_lshrrev_b64 v[66:67], 1, v[122:123]
	v_lshrrev_b64 v[64:65], 1, v[102:103]
	v_lshl_add_u64 v[98:99], v[172:173], 0, s[20:21]
	s_mov_b32 s20, 0x58000
	v_lshl_add_u64 v[120:121], s[12:13], 0, v[66:67]
	v_lshrrev_b64 v[66:67], 1, v[114:115]
	v_lshl_add_u64 v[100:101], s[12:13], 0, v[64:65]
	v_add_co_u32_e32 v64, vcc, s20, v170
	s_mov_b64 s[20:21], 0x2c080
	v_lshl_add_u64 v[112:113], s[12:13], 0, v[66:67]
	v_lshrrev_b64 v[66:67], 1, v[106:107]
	v_lshl_add_u64 v[94:95], v[172:173], 0, s[20:21]
	v_lshl_add_u64 v[104:105], s[12:13], 0, v[66:67]
	v_addc_co_u32_e32 v65, vcc, 0, v171, vcc
	v_lshrrev_b64 v[66:67], 1, v[98:99]
	v_lshrrev_b64 v[92:93], 1, v[94:95]
	v_lshl_add_u64 v[96:97], s[12:13], 0, v[66:67]
	s_nop 0
	v_lshl_add_u64 v[92:93], s[12:13], 0, v[92:93]
	s_waitcnt vmcnt(0) lgkmcnt(0)
	v_mov_b32_e32 v132, v240
	v_mov_b32_e32 v133, v241
	v_mov_b32_e32 v134, v242
	v_mov_b32_e32 v135, v243
	v_mov_b32_e32 v88, v244
	v_mov_b32_e32 v89, v245
	v_mov_b32_e32 v90, v246
	v_mov_b32_e32 v91, v247
	v_mov_b32_e32 v84, v152
	v_mov_b32_e32 v85, v153
	v_mov_b32_e32 v86, v154
	v_mov_b32_e32 v87, v155
	v_mov_b32_e32 v80, v198
	v_mov_b32_e32 v81, v199
	v_mov_b32_e32 v82, v200
	v_mov_b32_e32 v83, v201
	v_mov_b32_e32 v76, v202
	v_mov_b32_e32 v77, v203
	v_mov_b32_e32 v78, v204
	v_mov_b32_e32 v79, v205
	v_mov_b32_e32 v72, v220
	v_mov_b32_e32 v73, v221
	v_mov_b32_e32 v74, v222
	v_mov_b32_e32 v75, v223
	v_mov_b32_e32 v68, v224
	v_mov_b32_e32 v69, v225
	v_mov_b32_e32 v70, v226
	v_mov_b32_e32 v71, v227
	v_mov_b32_e32 v64, v228
	v_mov_b32_e32 v65, v229
	v_mov_b32_e32 v66, v230
	v_mov_b32_e32 v67, v231
	v_mov_b32_e32 v131, v233
	v_mov_b32_e32 v130, v234
	v_mov_b32_e32 v129, v235
	v_mov_b32_e32 v128, v249
	v_mov_b32_e32 v127, v250
	v_mov_b32_e32 v126, v251
	v_mov_b32_e32 v125, v147
	v_mov_b32_e32 v124, v218
	v_lshrrev_b32_e32 v138, 4, v131
	v_and_b32_e32 v138, 15, v138
	v_and_b32_e32 v139, 15, v131
	v_add_u32_e32 v141, -8, v139
	v_add_u32_e32 v138, -8, v138
	v_lshlrev_b32_e32 v136, 16, v132
	v_cvt_f32_i32_e32 v139, v138
	v_cvt_f32_i32_e32 v138, v141
	v_and_b32_e32 v137, 0xffff0000, v132
	v_and_b32_e32 v132, 0x7f800000, v132
	v_and_b32_e32 v140, 0x7f800000, v136
	v_max_u32_e32 v140, 0x6000000, v140
	v_max_u32_e32 v132, 0x6000000, v132
	v_add_u32_e32 v141, 0xfa800000, v132
	v_add_u32_e32 v140, 0xfa800000, v140
	v_pk_fma_f32 v[136:137], v[138:139], v[140:141], v[136:137]
	v_lshrrev_b32_e32 v132, 12, v131
	v_lshrrev_b32_e32 v138, 8, v131
	v_pk_fma_f32 v[60:61], v[60:61], s[46:47], v[136:137]
	v_lshlrev_b32_e32 v136, 16, v133
	v_and_b32_e32 v132, 15, v132
	v_and_b32_e32 v138, 15, v138
	v_and_b32_e32 v137, 0xffff0000, v133
	v_and_b32_e32 v139, 0x7f800000, v133
	v_and_b32_e32 v133, 0x7f800000, v136
	v_add_u32_e32 v138, -8, v138
	v_add_u32_e32 v132, -8, v132
	v_max_u32_e32 v140, 0x6000000, v133
	v_cvt_f32_i32_e32 v133, v132
	v_cvt_f32_i32_e32 v132, v138
	v_max_u32_e32 v138, 0x6000000, v139
	v_add_u32_e32 v139, 0xfa800000, v138
	v_add_u32_e32 v138, 0xfa800000, v140
	v_pk_fma_f32 v[132:133], v[132:133], v[138:139], v[136:137]
	v_lshrrev_b32_e32 v136, 20, v131
	v_and_b32_e32 v136, 15, v136
	v_and_b32_sdwa v137, v131, v237 dst_sel:DWORD dst_unused:UNUSED_PAD src0_sel:WORD_1 src1_sel:DWORD
	v_add_u32_e32 v139, -8, v137
	v_add_u32_e32 v136, -8, v136
	v_pk_fma_f32 v[62:63], v[62:63], s[46:47], v[132:133]
	v_lshlrev_b32_e32 v132, 16, v134
	v_cvt_f32_i32_e32 v137, v136
	v_cvt_f32_i32_e32 v136, v139
	v_and_b32_e32 v133, 0xffff0000, v134
	v_and_b32_e32 v134, 0x7f800000, v134
	v_and_b32_e32 v138, 0x7f800000, v132
	v_max_u32_e32 v138, 0x6000000, v138
	v_max_u32_e32 v134, 0x6000000, v134
	v_add_u32_e32 v139, 0xfa800000, v134
	v_add_u32_e32 v138, 0xfa800000, v138
	v_pk_fma_f32 v[132:133], v[136:137], v[138:139], v[132:133]
	v_bfe_u32 v134, v131, 24, 4
	v_pk_fma_f32 v[56:57], v[56:57], s[46:47], v[132:133]
	v_lshrrev_b32_e32 v131, 28, v131
	v_lshlrev_b32_e32 v132, 16, v135
	v_and_b32_e32 v133, 0xffff0000, v135
	v_and_b32_e32 v136, 0x7f800000, v135
	v_and_b32_e32 v135, 0x7f800000, v132
	v_add_u32_e32 v134, -8, v134
	v_add_u32_e32 v131, -8, v131
	v_max_u32_e32 v138, 0x6000000, v135
	v_cvt_f32_i32_e32 v135, v131
	v_cvt_f32_i32_e32 v134, v134
	v_max_u32_e32 v131, 0x6000000, v136
	v_add_u32_e32 v137, 0xfa800000, v131
	v_add_u32_e32 v136, 0xfa800000, v138
	v_pk_fma_f32 v[132:133], v[134:135], v[136:137], v[132:133]
	s_and_b64 vcc, exec, s[42:43]
	v_pk_fma_f32 v[58:59], v[58:59], s[46:47], v[132:133]
	s_mov_b64 s[20:21], -1
	s_cbranch_vccnz .LBB0_628
	v_lshl_add_u64 v[122:123], v[122:123], 2, s[6:7]
	s_mov_b64 s[20:21], 0
	global_store_dwordx4 v[122:123], v[60:63], off
	global_store_dwordx4 v[122:123], v[56:59], off offset:16
